# register parking without the one-lane placeholder loads/stores (the K-loop's counted waits do not depend on epilogue op counts)
# speedup vs baseline: 1.1249x; 1.0047x over previous
.LBB0_1060:
	s_cmp_gt_u32 s55, 1
	s_cselect_b64 s[26:27], -1, 0
	s_cmp_lt_u32 s55, 2
	v_mov_b32_e32 v178, 0
	v_mov_b32_e32 v186, 0
	v_mov_b32_e32 v187, 0
	v_mov_b32_e32 v188, 0
	v_mov_b32_e32 v189, 0
	s_cbranch_scc1 .LBB0_1062
	global_load_dwordx4 v[186:189], v[130:131], off
.LBB0_1062:
	v_cndmask_b32_e64 v130, 0, 1, s[26:27]
	v_cmp_ne_u32_e64 s[0:1], 1, v130
	s_andn2_b64 vcc, exec, s[26:27]
	v_mov_b32_e32 v179, 0
	v_mov_b32_e32 v180, 0
	v_mov_b32_e32 v181, 0
	s_cbranch_vccnz .LBB0_1064
	v_add_co_u32_e32 v130, vcc, 0x20000, v208
	s_nop 1
	v_addc_co_u32_e32 v131, vcc, 0, v209, vcc
	global_load_dwordx4 v[178:181], v[130:131], off offset:256
.LBB0_1064:
	v_add_co_u32_e32 v130, vcc, 0x2000, v208
	v_mov_b32_e32 v162, 0
	s_nop 0
	v_addc_co_u32_e32 v131, vcc, 0, v209, vcc
	s_and_b64 vcc, exec, s[0:1]
	v_mov_b32_e32 v170, 0
	v_mov_b32_e32 v171, 0
	v_mov_b32_e32 v172, 0
	v_mov_b32_e32 v173, 0
	s_cbranch_vccnz .LBB0_1066
	v_add_co_u32_e32 v130, vcc, 0x22000, v208
	s_nop 1
	v_addc_co_u32_e32 v131, vcc, 0, v209, vcc
	global_load_dwordx4 v[170:173], v[130:131], off
.LBB0_1066:
	v_add_co_u32_e32 v130, vcc, 0x2000, v208
	v_mov_b32_e32 v163, 0
	s_nop 0
	v_addc_co_u32_e32 v131, vcc, 0, v209, vcc
	s_and_b64 vcc, exec, s[0:1]
	v_mov_b32_e32 v164, 0
	v_mov_b32_e32 v165, 0
	s_cbranch_vccnz .LBB0_1068
	v_add_co_u32_e32 v130, vcc, 0x22000, v208
	s_nop 1
	v_addc_co_u32_e32 v131, vcc, 0, v209, vcc
	global_load_dwordx4 v[162:165], v[130:131], off offset:256
.LBB0_1068:
	v_add_co_u32_e32 v130, vcc, 0x4000, v208
	v_mov_b32_e32 v146, 0
	s_nop 0
	v_addc_co_u32_e32 v131, vcc, 0, v209, vcc
	s_and_b64 vcc, exec, s[0:1]
	v_mov_b32_e32 v154, 0
	v_mov_b32_e32 v155, 0
	v_mov_b32_e32 v156, 0
	v_mov_b32_e32 v157, 0
	s_cbranch_vccnz .LBB0_1070
	v_add_co_u32_e32 v130, vcc, 0x24000, v208
	s_nop 1
	v_addc_co_u32_e32 v131, vcc, 0, v209, vcc
	global_load_dwordx4 v[154:157], v[130:131], off
.LBB0_1070:
	v_add_co_u32_e32 v130, vcc, 0x4000, v208
	v_mov_b32_e32 v147, 0
	s_nop 0
	v_addc_co_u32_e32 v131, vcc, 0, v209, vcc
	s_and_b64 vcc, exec, s[0:1]
	v_mov_b32_e32 v148, 0
	v_mov_b32_e32 v149, 0
	s_cbranch_vccnz .LBB0_1072
	v_add_co_u32_e32 v130, vcc, 0x24000, v208
	s_nop 1
	v_addc_co_u32_e32 v131, vcc, 0, v209, vcc
	global_load_dwordx4 v[146:149], v[130:131], off offset:256
.LBB0_1072:
	v_add_co_u32_e32 v130, vcc, 0x6000, v208
	v_mov_b32_e32 v138, 0
	s_nop 0
	v_addc_co_u32_e32 v131, vcc, 0, v209, vcc
	v_mov_b32_e32 v130, 0
	s_and_b64 vcc, exec, s[0:1]
	v_mov_b32_e32 v139, 0
	v_mov_b32_e32 v140, 0
	v_mov_b32_e32 v141, 0
	s_cbranch_vccnz .LBB0_1074
	v_add_co_u32_e32 v132, vcc, 0x26000, v208
	s_nop 1
	v_addc_co_u32_e32 v133, vcc, 0, v209, vcc
	global_load_dwordx4 v[138:141], v[132:133], off
.LBB0_1074:
	v_add_co_u32_e32 v132, vcc, 0x6000, v208
	v_mov_b32_e32 v131, 0
	s_nop 0
	v_addc_co_u32_e32 v133, vcc, 0, v209, vcc
	s_and_b64 vcc, exec, s[0:1]
	v_mov_b32_e32 v132, 0
	v_mov_b32_e32 v133, 0
	s_cbranch_vccnz .LBB0_1076
	v_add_co_u32_e32 v130, vcc, 0x26000, v208
	s_nop 1
	v_addc_co_u32_e32 v131, vcc, 0, v209, vcc
	global_load_dwordx4 v[130:133], v[130:131], off offset:256

.LBB0_1093:
	s_and_b64 vcc, exec, s[24:25]
	s_cbranch_vccz .LBB0_1049
	v_cvt_pk_bf16_f32 v110, v110, v111
	v_cvt_pk_bf16_f32 v111, v112, v113
	v_cvt_pk_bf16_f32 v112, v106, v107
	v_cvt_pk_bf16_f32 v113, v108, v109
	s_movk_i32 s0, 0x2000
	v_mov_b32_e32 v235, v110
	v_mov_b32_e32 v238, v111
	v_mov_b32_e32 v242, v112
	v_mov_b32_e32 v243, v113
	v_cvt_pk_bf16_f32 v94, v94, v95
	v_cvt_pk_bf16_f32 v95, v96, v97
	v_add_co_u32_e32 v110, vcc, s0, v208
	v_cvt_pk_bf16_f32 v96, v90, v91
	s_nop 0
	v_addc_co_u32_e32 v111, vcc, 0, v209, vcc
	v_cvt_pk_bf16_f32 v97, v92, v93
	s_movk_i32 s0, 0x4000
	v_mov_b32_e32 v248, v94
	v_mov_b32_e32 v249, v95
	v_mov_b32_e32 v250, v96
	v_mov_b32_e32 v251, v97
	v_cvt_pk_bf16_f32 v78, v78, v79
	v_cvt_pk_bf16_f32 v79, v80, v81
	v_add_co_u32_e32 v94, vcc, s0, v208
	v_cvt_pk_bf16_f32 v80, v74, v75
	s_nop 0
	v_addc_co_u32_e32 v95, vcc, 0, v209, vcc
	v_cvt_pk_bf16_f32 v81, v76, v77
	s_movk_i32 s0, 0x6000
	v_mov_b32_e32 v225, v78
	v_mov_b32_e32 v226, v79
	v_mov_b32_e32 v227, v80
	v_mov_b32_e32 v228, v81
	v_cvt_pk_bf16_f32 v62, v62, v63
	v_cvt_pk_bf16_f32 v63, v64, v65
	v_add_co_u32_e32 v78, vcc, s0, v208
	v_cvt_pk_bf16_f32 v64, v58, v59
	s_nop 0
	v_addc_co_u32_e32 v79, vcc, 0, v209, vcc
	v_add_co_u32_e32 v58, vcc, s89, v208
	v_cvt_pk_bf16_f32 v44, v44, v45
	s_nop 0
	v_addc_co_u32_e32 v59, vcc, 0, v209, vcc
	v_cvt_pk_bf16_f32 v45, v46, v47
	v_cvt_pk_bf16_f32 v46, v40, v41
	v_cvt_pk_bf16_f32 v47, v42, v43
	s_mov_b32 s0, 0x12000
	global_store_dwordx4 v[58:59], v[44:47], off offset:256
	v_cvt_pk_bf16_f32 v28, v28, v29
	v_cvt_pk_bf16_f32 v29, v30, v31
	v_add_co_u32_e32 v44, vcc, s0, v208
	v_cvt_pk_bf16_f32 v30, v24, v25
	s_nop 0
	v_addc_co_u32_e32 v45, vcc, 0, v209, vcc
	v_cvt_pk_bf16_f32 v31, v26, v27
	s_mov_b32 s0, 0x14000
	global_store_dwordx4 v[44:45], v[28:31], off offset:256
	v_cvt_pk_bf16_f32 v12, v12, v13
	v_cvt_pk_bf16_f32 v13, v14, v15
	v_add_co_u32_e32 v28, vcc, s0, v208
	v_cvt_pk_bf16_f32 v14, v8, v9
	s_nop 0
	v_addc_co_u32_e32 v29, vcc, 0, v209, vcc
	v_cvt_pk_bf16_f32 v15, v10, v11
	s_mov_b32 s0, 0x16000
	global_store_dwordx4 v[28:29], v[12:15], off offset:256
	v_cvt_pk_bf16_f32 v126, v126, v127
	v_cvt_pk_bf16_f32 v127, v128, v129
	v_add_co_u32_e32 v12, vcc, s0, v208
	v_cvt_pk_bf16_f32 v128, v122, v123
	v_cvt_pk_bf16_f32 v129, v124, v125
	v_cvt_pk_bf16_f32 v106, v118, v119
	v_cvt_pk_bf16_f32 v107, v120, v121
	v_cvt_pk_bf16_f32 v108, v114, v115
	v_cvt_pk_bf16_f32 v109, v116, v117
	v_cvt_pk_bf16_f32 v90, v102, v103
	v_cvt_pk_bf16_f32 v91, v104, v105
	v_cvt_pk_bf16_f32 v92, v98, v99
	v_cvt_pk_bf16_f32 v93, v100, v101
	v_cvt_pk_bf16_f32 v74, v86, v87
	v_cvt_pk_bf16_f32 v75, v88, v89
	v_cvt_pk_bf16_f32 v76, v82, v83
	v_cvt_pk_bf16_f32 v77, v84, v85
	v_cvt_pk_bf16_f32 v70, v70, v71
	v_cvt_pk_bf16_f32 v71, v72, v73
	v_cvt_pk_bf16_f32 v72, v66, v67
	v_cvt_pk_bf16_f32 v73, v68, v69
	v_cvt_pk_bf16_f32 v65, v60, v61
	v_cvt_pk_bf16_f32 v40, v54, v55
	v_cvt_pk_bf16_f32 v41, v56, v57
	v_cvt_pk_bf16_f32 v42, v50, v51
	v_cvt_pk_bf16_f32 v43, v52, v53
	v_cvt_pk_bf16_f32 v24, v36, v37
	v_cvt_pk_bf16_f32 v25, v38, v39
	v_cvt_pk_bf16_f32 v26, v32, v33
	v_cvt_pk_bf16_f32 v27, v34, v35
	v_cvt_pk_bf16_f32 v8, v20, v21
	v_cvt_pk_bf16_f32 v9, v22, v23
	v_cvt_pk_bf16_f32 v10, v16, v17
	v_cvt_pk_bf16_f32 v11, v18, v19
	v_addc_co_u32_e32 v13, vcc, 0, v209, vcc
	v_cvt_pk_bf16_f32 v4, v4, v5
	v_cvt_pk_bf16_f32 v5, v6, v7
	v_cvt_pk_bf16_f32 v6, v0, v1
	v_cvt_pk_bf16_f32 v7, v2, v3
	v_mov_b32_e32 v222, v126
	v_mov_b32_e32 v223, v127
	v_mov_b32_e32 v233, v128
	v_mov_b32_e32 v234, v129
	v_mov_b32_e32 v244, v106
	v_mov_b32_e32 v245, v107
	v_mov_b32_e32 v246, v108
	v_mov_b32_e32 v247, v109
	v_mov_b32_e32 v194, v90
	v_mov_b32_e32 v195, v91
	v_mov_b32_e32 v196, v92
	v_mov_b32_e32 v197, v93
	v_mov_b32_e32 v229, v74
	v_mov_b32_e32 v230, v75
	v_mov_b32_e32 v231, v76
	v_mov_b32_e32 v232, v77
	v_mov_b32_e32 v236, v70
	v_mov_b32_e32 v237, v71
	v_mov_b32_e32 v239, v72
	v_mov_b32_e32 v240, v73
	global_store_dwordx4 v[58:59], v[62:65], off
	global_store_dwordx4 v[44:45], v[40:43], off
	global_store_dwordx4 v[28:29], v[24:27], off
	global_store_dwordx4 v[12:13], v[8:11], off
	global_store_dwordx4 v[12:13], v[4:7], off offset:256
	s_branch .LBB0_1049
